# prep: Z-fold item on f32 MFMA + modulation GEMV item with all loads in flight
# baseline (speedup 1.0000x reference)
.LBB0_49:
	s_and_b64 vcc, exec, s[40:41]
	s_cbranch_vccz .LBB0_78
	v_writelane_b32 v163, s0, 0
	v_writelane_b32 v163, s1, 1
	v_writelane_b32 v163, s2, 2
	v_writelane_b32 v163, s3, 3
	v_writelane_b32 v163, s4, 4
	v_writelane_b32 v163, s5, 5
	v_writelane_b32 v163, s6, 6
	v_writelane_b32 v163, s7, 7
	v_writelane_b32 v163, s8, 8
	v_writelane_b32 v163, s9, 9
	v_writelane_b32 v163, s10, 10
	v_writelane_b32 v163, s11, 11
	v_writelane_b32 v163, s12, 12
	v_writelane_b32 v163, s13, 13
	v_writelane_b32 v163, s14, 14
	v_writelane_b32 v163, s15, 15
	s_add_i32 s0, s29, 0xffffff40
	s_lshr_b32 s1, s0, 6
	s_bfe_u32 s2, s0, 0x20004
	s_and_b32 s3, s0, 15
	s_lshl_b32 s3, s3, 6
	v_readlane_b32 s4, v251, 40
	v_readlane_b32 s5, v251, 41
	v_readlane_b32 s8, v251, 18
	v_readlane_b32 s9, v251, 19
	v_mbcnt_lo_u32_b32 v160, -1, 0
	v_mbcnt_hi_u32_b32 v160, -1, v160
	v_and_b32_e32 v162, 15, v160
	v_lshrrev_b32_e32 v210, 4, v160
	v_readfirstlane_b32 s10, v76
	s_lshr_b32 s10, s10, 6
	s_lshl_b32 s11, s1, 10
	s_add_i32 s11, s11, s3
	s_mul_i32 s11, s11, 0x2800
	s_lshl_b32 s12, s2, 8
	s_add_i32 s11, s11, s12
	s_add_i32 s11, s11, 0x2400
	s_add_u32 s4, s4, s11
	s_addc_u32 s5, s5, 0
	s_mul_i32 s11, s1, 0x1800000
	s_add_u32 s8, s8, s11
	s_addc_u32 s9, s9, 0
	s_add_u32 s8, s8, 0x100000
	s_addc_u32 s9, s9, 0
	v_mul_u32_u24_e32 v248, 0x2800, v162
	v_lshl_add_u32 v248, v210, 4, v248
	global_load_dwordx4 v[188:191], v248, s[4:5]
	global_load_dwordx4 v[192:195], v248, s[4:5] offset:64
	global_load_dwordx4 v[196:199], v248, s[4:5] offset:128
	global_load_dwordx4 v[200:203], v248, s[4:5] offset:192
	s_add_u32 s12, s4, 0x28000
	s_addc_u32 s13, s5, 0
	global_load_dwordx4 v[204:207], v248, s[12:13]
	global_load_dwordx4 v[212:215], v248, s[12:13] offset:64
	global_load_dwordx4 v[220:223], v248, s[12:13] offset:128
	global_load_dwordx4 v[224:227], v248, s[12:13] offset:192
	s_add_u32 s12, s4, 0x50000
	s_addc_u32 s13, s5, 0
	global_load_dwordx4 v[228:231], v248, s[12:13]
	global_load_dwordx4 v[232:235], v248, s[12:13] offset:64
	global_load_dwordx4 v[236:239], v248, s[12:13] offset:128
	global_load_dwordx4 v[240:243], v248, s[12:13] offset:192
	v_mov_b32_e32 v152, 0
	v_mov_b32_e32 v153, 0
	v_mov_b32_e32 v154, 0
	v_mov_b32_e32 v155, 0
	v_mov_b32_e32 v156, 0
	v_mov_b32_e32 v157, 0
	v_mov_b32_e32 v158, 0
	v_mov_b32_e32 v159, 0
	v_mov_b32_e32 v164, 0
	v_mov_b32_e32 v165, 0
	v_mov_b32_e32 v166, 0
	v_mov_b32_e32 v167, 0
	v_mov_b32_e32 v168, 0
	v_mov_b32_e32 v169, 0
	v_mov_b32_e32 v170, 0
	v_mov_b32_e32 v171, 0
	s_lshl_b32 s11, s10, 4
	v_add_u32_e32 v211, s11, v162
	v_and_b32_e32 v244, 1, v211
	v_lshrrev_b32_e32 v211, 1, v211
	v_cmp_eq_u32_e32 vcc, 1, v244
	v_lshl_add_u32 v245, v210, 2, 0
	v_mul_u32_u24_e32 v245, v245, v211
	v_and_b32_e32 v245, 63, v245
	v_cvt_f32_u32_e32 v245, v245
	v_mul_f32_e32 v245, 0x3c800000, v245
	v_cos_f32_e32 v246, v245
	v_sin_f32_e32 v245, v245
	s_nop 0
	v_mul_f32_e32 v246, 0x3e000000, v246
	v_mul_f32_e32 v245, 0xbe000000, v245
	v_cndmask_b32_e32 v172, v246, v245, vcc
	v_lshl_add_u32 v245, v210, 2, 1
	v_mul_u32_u24_e32 v245, v245, v211
	v_and_b32_e32 v245, 63, v245
	v_cvt_f32_u32_e32 v245, v245
	v_mul_f32_e32 v245, 0x3c800000, v245
	v_cos_f32_e32 v246, v245
	v_sin_f32_e32 v245, v245
	s_nop 0
	v_mul_f32_e32 v246, 0x3e000000, v246
	v_mul_f32_e32 v245, 0xbe000000, v245
	v_cndmask_b32_e32 v173, v246, v245, vcc
	v_lshl_add_u32 v245, v210, 2, 2
	v_mul_u32_u24_e32 v245, v245, v211
	v_and_b32_e32 v245, 63, v245
	v_cvt_f32_u32_e32 v245, v245
	v_mul_f32_e32 v245, 0x3c800000, v245
	v_cos_f32_e32 v246, v245
	v_sin_f32_e32 v245, v245
	s_nop 0
	v_mul_f32_e32 v246, 0x3e000000, v246
	v_mul_f32_e32 v245, 0xbe000000, v245
	v_cndmask_b32_e32 v174, v246, v245, vcc
	v_lshl_add_u32 v245, v210, 2, 3
	v_mul_u32_u24_e32 v245, v245, v211
	v_and_b32_e32 v245, 63, v245
	v_cvt_f32_u32_e32 v245, v245
	v_mul_f32_e32 v245, 0x3c800000, v245
	v_cos_f32_e32 v246, v245
	v_sin_f32_e32 v245, v245
	s_nop 0
	v_mul_f32_e32 v246, 0x3e000000, v246
	v_mul_f32_e32 v245, 0xbe000000, v245
	v_cndmask_b32_e32 v175, v246, v245, vcc
	v_lshl_add_u32 v245, v210, 2, 16
	v_mul_u32_u24_e32 v245, v245, v211
	v_and_b32_e32 v245, 63, v245
	v_cvt_f32_u32_e32 v245, v245
	v_mul_f32_e32 v245, 0x3c800000, v245
	v_cos_f32_e32 v246, v245
	v_sin_f32_e32 v245, v245
	s_nop 0
	v_mul_f32_e32 v246, 0x3e000000, v246
	v_mul_f32_e32 v245, 0xbe000000, v245
	v_cndmask_b32_e32 v176, v246, v245, vcc
	v_lshl_add_u32 v245, v210, 2, 17
	v_mul_u32_u24_e32 v245, v245, v211
	v_and_b32_e32 v245, 63, v245
	v_cvt_f32_u32_e32 v245, v245
	v_mul_f32_e32 v245, 0x3c800000, v245
	v_cos_f32_e32 v246, v245
	v_sin_f32_e32 v245, v245
	s_nop 0
	v_mul_f32_e32 v246, 0x3e000000, v246
	v_mul_f32_e32 v245, 0xbe000000, v245
	v_cndmask_b32_e32 v177, v246, v245, vcc
	v_lshl_add_u32 v245, v210, 2, 18
	v_mul_u32_u24_e32 v245, v245, v211
	v_and_b32_e32 v245, 63, v245
	v_cvt_f32_u32_e32 v245, v245
	v_mul_f32_e32 v245, 0x3c800000, v245
	v_cos_f32_e32 v246, v245
	v_sin_f32_e32 v245, v245
	s_nop 0
	v_mul_f32_e32 v246, 0x3e000000, v246
	v_mul_f32_e32 v245, 0xbe000000, v245
	v_cndmask_b32_e32 v178, v246, v245, vcc
	v_lshl_add_u32 v245, v210, 2, 19
	v_mul_u32_u24_e32 v245, v245, v211
	v_and_b32_e32 v245, 63, v245
	v_cvt_f32_u32_e32 v245, v245
	v_mul_f32_e32 v245, 0x3c800000, v245
	v_cos_f32_e32 v246, v245
	v_sin_f32_e32 v245, v245
	s_nop 0
	v_mul_f32_e32 v246, 0x3e000000, v246
	v_mul_f32_e32 v245, 0xbe000000, v245
	v_cndmask_b32_e32 v179, v246, v245, vcc
	v_lshl_add_u32 v245, v210, 2, 32
	v_mul_u32_u24_e32 v245, v245, v211
	v_and_b32_e32 v245, 63, v245
	v_cvt_f32_u32_e32 v245, v245
	v_mul_f32_e32 v245, 0x3c800000, v245
	v_cos_f32_e32 v246, v245
	v_sin_f32_e32 v245, v245
	s_nop 0
	v_mul_f32_e32 v246, 0x3e000000, v246
	v_mul_f32_e32 v245, 0xbe000000, v245
	v_cndmask_b32_e32 v180, v246, v245, vcc
	v_lshl_add_u32 v245, v210, 2, 33
	v_mul_u32_u24_e32 v245, v245, v211
	v_and_b32_e32 v245, 63, v245
	v_cvt_f32_u32_e32 v245, v245
	v_mul_f32_e32 v245, 0x3c800000, v245
	v_cos_f32_e32 v246, v245
	v_sin_f32_e32 v245, v245
	s_nop 0
	v_mul_f32_e32 v246, 0x3e000000, v246
	v_mul_f32_e32 v245, 0xbe000000, v245
	v_cndmask_b32_e32 v181, v246, v245, vcc
	v_lshl_add_u32 v245, v210, 2, 34
	v_mul_u32_u24_e32 v245, v245, v211
	v_and_b32_e32 v245, 63, v245
	v_cvt_f32_u32_e32 v245, v245
	v_mul_f32_e32 v245, 0x3c800000, v245
	v_cos_f32_e32 v246, v245
	v_sin_f32_e32 v245, v245
	s_nop 0
	v_mul_f32_e32 v246, 0x3e000000, v246
	v_mul_f32_e32 v245, 0xbe000000, v245
	v_cndmask_b32_e32 v182, v246, v245, vcc
	v_lshl_add_u32 v245, v210, 2, 35
	v_mul_u32_u24_e32 v245, v245, v211
	v_and_b32_e32 v245, 63, v245
	v_cvt_f32_u32_e32 v245, v245
	v_mul_f32_e32 v245, 0x3c800000, v245
	v_cos_f32_e32 v246, v245
	v_sin_f32_e32 v245, v245
	s_nop 0
	v_mul_f32_e32 v246, 0x3e000000, v246
	v_mul_f32_e32 v245, 0xbe000000, v245
	v_cndmask_b32_e32 v183, v246, v245, vcc
	v_lshl_add_u32 v245, v210, 2, 48
	v_mul_u32_u24_e32 v245, v245, v211
	v_and_b32_e32 v245, 63, v245
	v_cvt_f32_u32_e32 v245, v245
	v_mul_f32_e32 v245, 0x3c800000, v245
	v_cos_f32_e32 v246, v245
	v_sin_f32_e32 v245, v245
	s_nop 0
	v_mul_f32_e32 v246, 0x3e000000, v246
	v_mul_f32_e32 v245, 0xbe000000, v245
	v_cndmask_b32_e32 v184, v246, v245, vcc
	v_lshl_add_u32 v245, v210, 2, 49
	v_mul_u32_u24_e32 v245, v245, v211
	v_and_b32_e32 v245, 63, v245
	v_cvt_f32_u32_e32 v245, v245
	v_mul_f32_e32 v245, 0x3c800000, v245
	v_cos_f32_e32 v246, v245
	v_sin_f32_e32 v245, v245
	s_nop 0
	v_mul_f32_e32 v246, 0x3e000000, v246
	v_mul_f32_e32 v245, 0xbe000000, v245
	v_cndmask_b32_e32 v185, v246, v245, vcc
	v_lshl_add_u32 v245, v210, 2, 50
	v_mul_u32_u24_e32 v245, v245, v211
	v_and_b32_e32 v245, 63, v245
	v_cvt_f32_u32_e32 v245, v245
	v_mul_f32_e32 v245, 0x3c800000, v245
	v_cos_f32_e32 v246, v245
	v_sin_f32_e32 v245, v245
	s_nop 0
	v_mul_f32_e32 v246, 0x3e000000, v246
	v_mul_f32_e32 v245, 0xbe000000, v245
	v_cndmask_b32_e32 v186, v246, v245, vcc
	v_lshl_add_u32 v245, v210, 2, 51
	v_mul_u32_u24_e32 v245, v245, v211
	v_and_b32_e32 v245, 63, v245
	v_cvt_f32_u32_e32 v245, v245
	v_mul_f32_e32 v245, 0x3c800000, v245
	v_cos_f32_e32 v246, v245
	v_sin_f32_e32 v245, v245
	s_nop 0
	v_mul_f32_e32 v246, 0x3e000000, v246
	v_mul_f32_e32 v245, 0xbe000000, v245
	v_cndmask_b32_e32 v187, v246, v245, vcc
	s_waitcnt vmcnt(4)
	v_mfma_f32_16x16x4_f32 v[152:155], v188, v172, v[152:155]
	v_mfma_f32_16x16x4_f32 v[156:159], v204, v172, v[156:159]
	v_mfma_f32_16x16x4_f32 v[152:155], v189, v173, v[152:155]
	v_mfma_f32_16x16x4_f32 v[156:159], v205, v173, v[156:159]
	v_mfma_f32_16x16x4_f32 v[152:155], v190, v174, v[152:155]
	v_mfma_f32_16x16x4_f32 v[156:159], v206, v174, v[156:159]
	v_mfma_f32_16x16x4_f32 v[152:155], v191, v175, v[152:155]
	v_mfma_f32_16x16x4_f32 v[156:159], v207, v175, v[156:159]
	v_mfma_f32_16x16x4_f32 v[152:155], v192, v176, v[152:155]
	v_mfma_f32_16x16x4_f32 v[156:159], v212, v176, v[156:159]
	v_mfma_f32_16x16x4_f32 v[152:155], v193, v177, v[152:155]
	v_mfma_f32_16x16x4_f32 v[156:159], v213, v177, v[156:159]
	v_mfma_f32_16x16x4_f32 v[152:155], v194, v178, v[152:155]
	v_mfma_f32_16x16x4_f32 v[156:159], v214, v178, v[156:159]
	v_mfma_f32_16x16x4_f32 v[152:155], v195, v179, v[152:155]
	v_mfma_f32_16x16x4_f32 v[156:159], v215, v179, v[156:159]
	v_mfma_f32_16x16x4_f32 v[152:155], v196, v180, v[152:155]
	v_mfma_f32_16x16x4_f32 v[156:159], v220, v180, v[156:159]
	v_mfma_f32_16x16x4_f32 v[152:155], v197, v181, v[152:155]
	v_mfma_f32_16x16x4_f32 v[156:159], v221, v181, v[156:159]
	v_mfma_f32_16x16x4_f32 v[152:155], v198, v182, v[152:155]
	v_mfma_f32_16x16x4_f32 v[156:159], v222, v182, v[156:159]
	v_mfma_f32_16x16x4_f32 v[152:155], v199, v183, v[152:155]
	v_mfma_f32_16x16x4_f32 v[156:159], v223, v183, v[156:159]
	v_mfma_f32_16x16x4_f32 v[152:155], v200, v184, v[152:155]
	v_mfma_f32_16x16x4_f32 v[156:159], v224, v184, v[156:159]
	v_mfma_f32_16x16x4_f32 v[152:155], v201, v185, v[152:155]
	v_mfma_f32_16x16x4_f32 v[156:159], v225, v185, v[156:159]
	v_mfma_f32_16x16x4_f32 v[152:155], v202, v186, v[152:155]
	v_mfma_f32_16x16x4_f32 v[156:159], v226, v186, v[156:159]
	v_mfma_f32_16x16x4_f32 v[152:155], v203, v187, v[152:155]
	v_mfma_f32_16x16x4_f32 v[156:159], v227, v187, v[156:159]
	s_add_u32 s12, s4, 0x78000
	s_addc_u32 s13, s5, 0
	global_load_dwordx4 v[188:191], v248, s[12:13]
	global_load_dwordx4 v[192:195], v248, s[12:13] offset:64
	global_load_dwordx4 v[196:199], v248, s[12:13] offset:128
	global_load_dwordx4 v[200:203], v248, s[12:13] offset:192
	s_waitcnt vmcnt(4)
	v_mfma_f32_16x16x4_f32 v[164:167], v228, v172, v[164:167]
	v_mfma_f32_16x16x4_f32 v[164:167], v229, v173, v[164:167]
	v_mfma_f32_16x16x4_f32 v[164:167], v230, v174, v[164:167]
	v_mfma_f32_16x16x4_f32 v[164:167], v231, v175, v[164:167]
	v_mfma_f32_16x16x4_f32 v[164:167], v232, v176, v[164:167]
	v_mfma_f32_16x16x4_f32 v[164:167], v233, v177, v[164:167]
	v_mfma_f32_16x16x4_f32 v[164:167], v234, v178, v[164:167]
	v_mfma_f32_16x16x4_f32 v[164:167], v235, v179, v[164:167]
	v_mfma_f32_16x16x4_f32 v[164:167], v236, v180, v[164:167]
	v_mfma_f32_16x16x4_f32 v[164:167], v237, v181, v[164:167]
	v_mfma_f32_16x16x4_f32 v[164:167], v238, v182, v[164:167]
	v_mfma_f32_16x16x4_f32 v[164:167], v239, v183, v[164:167]
	v_mfma_f32_16x16x4_f32 v[164:167], v240, v184, v[164:167]
	v_mfma_f32_16x16x4_f32 v[164:167], v241, v185, v[164:167]
	v_mfma_f32_16x16x4_f32 v[164:167], v242, v186, v[164:167]
	v_mfma_f32_16x16x4_f32 v[164:167], v243, v187, v[164:167]
	s_waitcnt vmcnt(0)
	v_mfma_f32_16x16x4_f32 v[168:171], v188, v172, v[168:171]
	v_mfma_f32_16x16x4_f32 v[168:171], v189, v173, v[168:171]
	v_mfma_f32_16x16x4_f32 v[168:171], v190, v174, v[168:171]
	v_mfma_f32_16x16x4_f32 v[168:171], v191, v175, v[168:171]
	v_mfma_f32_16x16x4_f32 v[168:171], v192, v176, v[168:171]
	v_mfma_f32_16x16x4_f32 v[168:171], v193, v177, v[168:171]
	v_mfma_f32_16x16x4_f32 v[168:171], v194, v178, v[168:171]
	v_mfma_f32_16x16x4_f32 v[168:171], v195, v179, v[168:171]
	v_mfma_f32_16x16x4_f32 v[168:171], v196, v180, v[168:171]
	v_mfma_f32_16x16x4_f32 v[168:171], v197, v181, v[168:171]
	v_mfma_f32_16x16x4_f32 v[168:171], v198, v182, v[168:171]
	v_mfma_f32_16x16x4_f32 v[168:171], v199, v183, v[168:171]
	v_mfma_f32_16x16x4_f32 v[168:171], v200, v184, v[168:171]
	v_mfma_f32_16x16x4_f32 v[168:171], v201, v185, v[168:171]
	v_mfma_f32_16x16x4_f32 v[168:171], v202, v186, v[168:171]
	v_mfma_f32_16x16x4_f32 v[168:171], v203, v187, v[168:171]
	s_nop 7
	s_nop 7
	s_lshl_b32 s12, s2, 7
	s_add_i32 s11, s11, s12
	s_add_i32 s11, s11, 0x900
	v_add_u32_e32 v249, s11, v162
	v_lshlrev_b32_e32 v249, 10, v249
	v_lshl_add_u32 v249, v210, 2, v249
	v_add_u32_e32 v249, s3, v249
	v_lshlrev_b32_e32 v249, 1, v249
	v_cvt_pk_bf16_f32 v152, v152, v153
	v_cvt_pk_bf16_f32 v153, v154, v155
	v_cvt_pk_bf16_f32 v156, v156, v157
	v_cvt_pk_bf16_f32 v157, v158, v159
	v_cvt_pk_bf16_f32 v164, v164, v165
	v_cvt_pk_bf16_f32 v165, v166, v167
	v_cvt_pk_bf16_f32 v168, v168, v169
	v_cvt_pk_bf16_f32 v169, v170, v171
	global_store_dwordx2 v249, v[152:153], s[8:9]
	global_store_dwordx2 v249, v[156:157], s[8:9] offset:32
	global_store_dwordx2 v249, v[164:165], s[8:9] offset:64
	global_store_dwordx2 v249, v[168:169], s[8:9] offset:96
	v_readlane_b32 s0, v163, 0
	v_readlane_b32 s1, v163, 1
	v_readlane_b32 s2, v163, 2
	v_readlane_b32 s3, v163, 3
	v_readlane_b32 s4, v163, 4
	v_readlane_b32 s5, v163, 5
	v_readlane_b32 s6, v163, 6
	v_readlane_b32 s7, v163, 7
	v_readlane_b32 s8, v163, 8
	v_readlane_b32 s9, v163, 9
	v_readlane_b32 s10, v163, 10
	v_readlane_b32 s11, v163, 11
	v_readlane_b32 s12, v163, 12
	v_readlane_b32 s13, v163, 13
	v_readlane_b32 s14, v163, 14
	v_readlane_b32 s15, v163, 15
	s_nop 3
	s_mov_b64 s[40:41], 0

.LBB0_68:
	s_and_saveexec_b64 s[40:41], s[74:75]
	v_readlane_b32 s44, v251, 26
	v_readlane_b32 s50, v251, 32
	v_readlane_b32 s51, v251, 33
	v_readlane_b32 s45, v251, 27
	v_readlane_b32 s46, v251, 28
	v_readlane_b32 s47, v251, 29
	v_readlane_b32 s48, v251, 30
	v_readlane_b32 s49, v251, 31
	v_readlane_b32 s52, v251, 34
	v_readlane_b32 s53, v251, 35
	v_readlane_b32 s54, v251, 36
	v_readlane_b32 s55, v251, 37
	v_readlane_b32 s56, v251, 38
	v_readlane_b32 s57, v251, 39
	v_readlane_b32 s58, v251, 40
	v_readlane_b32 s59, v251, 41
	s_or_b64 exec, exec, s[40:41]
	s_cmpk_gt_u32 s29, 0x5f
	s_cselect_b64 s[40:41], -1, 0
	s_lshl_b32 s0, s29, 6
	s_add_i32 s1, s0, 0xffffe800
	s_cmpk_lt_u32 s29, 0x60
	s_cselect_b32 s38, s0, s1
	s_and_b64 s[0:1], s[40:41], exec
	s_cselect_b32 s2, 0x1800000, 0
	s_lshl_b64 s[0:1], s[38:39], 2
	s_add_u32 s0, s2, s0
	s_addc_u32 s1, 0, s1
	s_add_u32 s42, s52, s0
	s_addc_u32 s43, s53, s1
	v_lshlrev_b32_e32 v17, 2, v76
	v_lshrrev_b32_e32 v19, 4, v76
	v_and_b32_e32 v16, 15, v76
	v_lshlrev_b32_e32 v16, 4, v16
	v_mul_u32_u24_e32 v18, 0x6000, v19
	v_add_u32_e32 v16, v18, v16
	v_lshlrev_b32_e32 v19, 2, v19
	v_add_u32_e32 v18, 0x1000, v17
	global_load_dword v236, v17, s[46:47]
	global_load_dword v237, v17, s[46:47] offset:2048
	global_load_dword v238, v18, s[46:47]
	global_load_dword v239, v18, s[46:47] offset:2048
	global_load_dword v240, v17, s[50:51]
	global_load_dword v241, v17, s[50:51] offset:2048
	global_load_dwordx4 v[12:15], v16, s[42:43]
	s_add_u32 s42, s42, 0xc0000
	s_addc_u32 s43, s43, 0
	global_load_dwordx4 v[20:23], v16, s[42:43]
	s_add_u32 s42, s42, 0xc0000
	s_addc_u32 s43, s43, 0
	global_load_dwordx4 v[24:27], v16, s[42:43]
	s_add_u32 s42, s42, 0xc0000
	s_addc_u32 s43, s43, 0
	global_load_dwordx4 v[28:31], v16, s[42:43]
	s_add_u32 s42, s42, 0xc0000
	s_addc_u32 s43, s43, 0
	global_load_dwordx4 v[32:35], v16, s[42:43]
	s_add_u32 s42, s42, 0xc0000
	s_addc_u32 s43, s43, 0
	global_load_dwordx4 v[36:39], v16, s[42:43]
	s_add_u32 s42, s42, 0xc0000
	s_addc_u32 s43, s43, 0
	global_load_dwordx4 v[40:43], v16, s[42:43]
	s_add_u32 s42, s42, 0xc0000
	s_addc_u32 s43, s43, 0
	global_load_dwordx4 v[44:47], v16, s[42:43]
	s_add_u32 s42, s42, 0xc0000
	s_addc_u32 s43, s43, 0
	global_load_dwordx4 v[48:51], v16, s[42:43]
	s_add_u32 s42, s42, 0xc0000
	s_addc_u32 s43, s43, 0
	global_load_dwordx4 v[52:55], v16, s[42:43]
	s_add_u32 s42, s42, 0xc0000
	s_addc_u32 s43, s43, 0
	global_load_dwordx4 v[56:59], v16, s[42:43]
	s_add_u32 s42, s42, 0xc0000
	s_addc_u32 s43, s43, 0
	global_load_dwordx4 v[60:63], v16, s[42:43]
	s_add_u32 s42, s42, 0xc0000
	s_addc_u32 s43, s43, 0
	global_load_dwordx4 v[64:67], v16, s[42:43]
	s_add_u32 s42, s42, 0xc0000
	s_addc_u32 s43, s43, 0
	global_load_dwordx4 v[68:71], v16, s[42:43]
	s_add_u32 s42, s42, 0xc0000
	s_addc_u32 s43, s43, 0
	global_load_dwordx4 v[152:155], v16, s[42:43]
	s_add_u32 s42, s42, 0xc0000
	s_addc_u32 s43, s43, 0
	global_load_dwordx4 v[156:159], v16, s[42:43]
	s_add_u32 s42, s42, 0xc0000
	s_addc_u32 s43, s43, 0
	global_load_dwordx4 v[164:167], v16, s[42:43]
	s_add_u32 s42, s42, 0xc0000
	s_addc_u32 s43, s43, 0
	global_load_dwordx4 v[168:171], v16, s[42:43]
	s_add_u32 s42, s42, 0xc0000
	s_addc_u32 s43, s43, 0
	global_load_dwordx4 v[172:175], v16, s[42:43]
	s_add_u32 s42, s42, 0xc0000
	s_addc_u32 s43, s43, 0
	global_load_dwordx4 v[176:179], v16, s[42:43]
	s_add_u32 s42, s42, 0xc0000
	s_addc_u32 s43, s43, 0
	global_load_dwordx4 v[180:183], v16, s[42:43]
	s_add_u32 s42, s42, 0xc0000
	s_addc_u32 s43, s43, 0
	global_load_dwordx4 v[184:187], v16, s[42:43]
	s_add_u32 s42, s42, 0xc0000
	s_addc_u32 s43, s43, 0
	global_load_dwordx4 v[188:191], v16, s[42:43]
	s_add_u32 s42, s42, 0xc0000
	s_addc_u32 s43, s43, 0
	global_load_dwordx4 v[192:195], v16, s[42:43]
	s_add_u32 s42, s42, 0xc0000
	s_addc_u32 s43, s43, 0
	global_load_dwordx4 v[196:199], v16, s[42:43]
	s_add_u32 s42, s42, 0xc0000
	s_addc_u32 s43, s43, 0
	global_load_dwordx4 v[200:203], v16, s[42:43]
	s_add_u32 s42, s42, 0xc0000
	s_addc_u32 s43, s43, 0
	global_load_dwordx4 v[204:207], v16, s[42:43]
	s_add_u32 s42, s42, 0xc0000
	s_addc_u32 s43, s43, 0
	global_load_dwordx4 v[212:215], v16, s[42:43]
	s_add_u32 s42, s42, 0xc0000
	s_addc_u32 s43, s43, 0
	global_load_dwordx4 v[220:223], v16, s[42:43]
	s_add_u32 s42, s42, 0xc0000
	s_addc_u32 s43, s43, 0
	global_load_dwordx4 v[224:227], v16, s[42:43]
	s_add_u32 s42, s42, 0xc0000
	s_addc_u32 s43, s43, 0
	global_load_dwordx4 v[228:231], v16, s[42:43]
	s_add_u32 s42, s42, 0xc0000
	s_addc_u32 s43, s43, 0
	global_load_dwordx4 v[232:235], v16, s[42:43]
	s_waitcnt vmcnt(32)
	v_mul_f32_e32 v5, 0xbfb8aa3b, v236
	v_exp_f32_e32 v5, v5
	s_nop 0
	v_add_f32_e32 v5, 1.0, v5
	v_div_scale_f32 v6, s[0:1], v5, v5, v236
	v_rcp_f32_e32 v7, v6
	v_div_scale_f32 v8, vcc, v236, v5, v236
	v_fma_f32 v9, -v6, v7, 1.0
	v_fmac_f32_e32 v7, v9, v7
	v_mul_f32_e32 v9, v8, v7
	v_fma_f32 v10, -v6, v9, v8
	v_fmac_f32_e32 v9, v10, v7
	v_fma_f32 v6, -v6, v9, v8
	v_div_fmas_f32 v6, v6, v7, v9
	v_div_fixup_f32 v4, v6, v5, v236
	ds_write_b32 v17, v4
	v_mul_f32_e32 v5, 0xbfb8aa3b, v237
	v_exp_f32_e32 v5, v5
	s_nop 0
	v_add_f32_e32 v5, 1.0, v5
	v_div_scale_f32 v6, s[0:1], v5, v5, v237
	v_rcp_f32_e32 v7, v6
	v_div_scale_f32 v8, vcc, v237, v5, v237
	v_fma_f32 v9, -v6, v7, 1.0
	v_fmac_f32_e32 v7, v9, v7
	v_mul_f32_e32 v9, v8, v7
	v_fma_f32 v10, -v6, v9, v8
	v_fmac_f32_e32 v9, v10, v7
	v_fma_f32 v6, -v6, v9, v8
	v_div_fmas_f32 v6, v6, v7, v9
	v_div_fixup_f32 v4, v6, v5, v237
	ds_write_b32 v17, v4 offset:2048
	v_mul_f32_e32 v5, 0xbfb8aa3b, v238
	v_exp_f32_e32 v5, v5
	s_nop 0
	v_add_f32_e32 v5, 1.0, v5
	v_div_scale_f32 v6, s[0:1], v5, v5, v238
	v_rcp_f32_e32 v7, v6
	v_div_scale_f32 v8, vcc, v238, v5, v238
	v_fma_f32 v9, -v6, v7, 1.0
	v_fmac_f32_e32 v7, v9, v7
	v_mul_f32_e32 v9, v8, v7
	v_fma_f32 v10, -v6, v9, v8
	v_fmac_f32_e32 v9, v10, v7
	v_fma_f32 v6, -v6, v9, v8
	v_div_fmas_f32 v6, v6, v7, v9
	v_div_fixup_f32 v4, v6, v5, v238
	ds_write_b32 v17, v4 offset:4096
	v_mul_f32_e32 v5, 0xbfb8aa3b, v239
	v_exp_f32_e32 v5, v5
	s_nop 0
	v_add_f32_e32 v5, 1.0, v5
	v_div_scale_f32 v6, s[0:1], v5, v5, v239
	v_rcp_f32_e32 v7, v6
	v_div_scale_f32 v8, vcc, v239, v5, v239
	v_fma_f32 v9, -v6, v7, 1.0
	v_fmac_f32_e32 v7, v9, v7
	v_mul_f32_e32 v9, v8, v7
	v_fma_f32 v10, -v6, v9, v8
	v_fmac_f32_e32 v9, v10, v7
	v_fma_f32 v6, -v6, v9, v8
	v_div_fmas_f32 v6, v6, v7, v9
	v_div_fixup_f32 v4, v6, v5, v239
	ds_write_b32 v17, v4 offset:6144
	v_mul_f32_e32 v5, 0xbfb8aa3b, v240
	v_exp_f32_e32 v5, v5
	s_nop 0
	v_add_f32_e32 v5, 1.0, v5
	v_div_scale_f32 v6, s[0:1], v5, v5, v240
	v_rcp_f32_e32 v7, v6
	v_div_scale_f32 v8, vcc, v240, v5, v240
	v_fma_f32 v9, -v6, v7, 1.0
	v_fmac_f32_e32 v7, v9, v7
	v_mul_f32_e32 v9, v8, v7
	v_fma_f32 v10, -v6, v9, v8
	v_fmac_f32_e32 v9, v10, v7
	v_fma_f32 v6, -v6, v9, v8
	v_div_fmas_f32 v6, v6, v7, v9
	v_div_fixup_f32 v4, v6, v5, v240
	ds_write_b32 v17, v4 offset:8192
	v_mul_f32_e32 v5, 0xbfb8aa3b, v241
	v_exp_f32_e32 v5, v5
	s_nop 0
	v_add_f32_e32 v5, 1.0, v5
	v_div_scale_f32 v6, s[0:1], v5, v5, v241
	v_rcp_f32_e32 v7, v6
	v_div_scale_f32 v8, vcc, v241, v5, v241
	v_fma_f32 v9, -v6, v7, 1.0
	v_fmac_f32_e32 v7, v9, v7
	v_mul_f32_e32 v9, v8, v7
	v_fma_f32 v10, -v6, v9, v8
	v_fmac_f32_e32 v9, v10, v7
	v_fma_f32 v6, -v6, v9, v8
	v_div_fmas_f32 v6, v6, v7, v9
	v_div_fixup_f32 v4, v6, v5, v241
	ds_write_b32 v17, v4 offset:10240
	v_mov_b32_e32 v0, 0
	v_mov_b32_e32 v1, 0
	v_mov_b32_e32 v2, 0
	v_mov_b32_e32 v3, 0
	v_mov_b32_e32 v4, 0
	v_mov_b32_e32 v5, 0
	v_mov_b32_e32 v6, 0
	v_mov_b32_e32 v7, 0
	v_mov_b32_e32 v8, 0
	v_mov_b32_e32 v9, 0
	v_mov_b32_e32 v10, 0
	v_mov_b32_e32 v11, 0
	s_waitcnt lgkmcnt(0)
	s_barrier
	ds_read_b32 v236, v19
	ds_read_b32 v237, v19 offset:4096
	ds_read_b32 v238, v19 offset:8192
	ds_read_b32 v239, v19 offset:128
	ds_read_b32 v240, v19 offset:4224
	ds_read_b32 v241, v19 offset:8320
	ds_read_b32 v242, v19 offset:256
	ds_read_b32 v243, v19 offset:4352
	ds_read_b32 v244, v19 offset:8448
	ds_read_b32 v245, v19 offset:384
	ds_read_b32 v246, v19 offset:4480
	ds_read_b32 v247, v19 offset:8576
	ds_read_b32 v210, v19 offset:512
	ds_read_b32 v211, v19 offset:4608
	ds_read_b32 v248, v19 offset:8704
	ds_read_b32 v249, v19 offset:640
	ds_read_b32 v160, v19 offset:4736
	ds_read_b32 v162, v19 offset:8832
	ds_read_b32 v72, v19 offset:768
	ds_read_b32 v74, v19 offset:4864
	ds_read_b32 v78, v19 offset:8960
	ds_read_b32 v96, v19 offset:896
	ds_read_b32 v98, v19 offset:4992
	ds_read_b32 v100, v19 offset:9088
	s_waitcnt lgkmcnt(12)
	s_waitcnt vmcnt(31)
	v_pk_fma_f32 v[4:5], v[12:13], v[236:237], v[4:5] op_sel_hi:[1,0,1]
	v_pk_fma_f32 v[6:7], v[14:15], v[236:237], v[6:7] op_sel_hi:[1,0,1]
	v_pk_fma_f32 v[8:9], v[12:13], v[236:237], v[8:9] op_sel:[0,1,0] op_sel_hi:[1,1,1]
	v_pk_fma_f32 v[10:11], v[14:15], v[236:237], v[10:11] op_sel:[0,1,0] op_sel_hi:[1,1,1]
	v_pk_fma_f32 v[0:1], v[12:13], v[238:239], v[0:1] op_sel_hi:[1,0,1]
	v_pk_fma_f32 v[2:3], v[14:15], v[238:239], v[2:3] op_sel_hi:[1,0,1]
	s_waitcnt vmcnt(30)
	v_pk_fma_f32 v[4:5], v[20:21], v[238:239], v[4:5] op_sel:[0,1,0] op_sel_hi:[1,1,1]
	v_pk_fma_f32 v[6:7], v[22:23], v[238:239], v[6:7] op_sel:[0,1,0] op_sel_hi:[1,1,1]
	v_pk_fma_f32 v[8:9], v[20:21], v[240:241], v[8:9] op_sel_hi:[1,0,1]
	v_pk_fma_f32 v[10:11], v[22:23], v[240:241], v[10:11] op_sel_hi:[1,0,1]
	v_pk_fma_f32 v[0:1], v[20:21], v[240:241], v[0:1] op_sel:[0,1,0] op_sel_hi:[1,1,1]
	v_pk_fma_f32 v[2:3], v[22:23], v[240:241], v[2:3] op_sel:[0,1,0] op_sel_hi:[1,1,1]
	s_waitcnt vmcnt(29)
	v_pk_fma_f32 v[4:5], v[24:25], v[242:243], v[4:5] op_sel_hi:[1,0,1]
	v_pk_fma_f32 v[6:7], v[26:27], v[242:243], v[6:7] op_sel_hi:[1,0,1]
	v_pk_fma_f32 v[8:9], v[24:25], v[242:243], v[8:9] op_sel:[0,1,0] op_sel_hi:[1,1,1]
	v_pk_fma_f32 v[10:11], v[26:27], v[242:243], v[10:11] op_sel:[0,1,0] op_sel_hi:[1,1,1]
	v_pk_fma_f32 v[0:1], v[24:25], v[244:245], v[0:1] op_sel_hi:[1,0,1]
	v_pk_fma_f32 v[2:3], v[26:27], v[244:245], v[2:3] op_sel_hi:[1,0,1]
	s_waitcnt vmcnt(28)
	v_pk_fma_f32 v[4:5], v[28:29], v[244:245], v[4:5] op_sel:[0,1,0] op_sel_hi:[1,1,1]
	v_pk_fma_f32 v[6:7], v[30:31], v[244:245], v[6:7] op_sel:[0,1,0] op_sel_hi:[1,1,1]
	v_pk_fma_f32 v[8:9], v[28:29], v[246:247], v[8:9] op_sel_hi:[1,0,1]
	v_pk_fma_f32 v[10:11], v[30:31], v[246:247], v[10:11] op_sel_hi:[1,0,1]
	v_pk_fma_f32 v[0:1], v[28:29], v[246:247], v[0:1] op_sel:[0,1,0] op_sel_hi:[1,1,1]
	v_pk_fma_f32 v[2:3], v[30:31], v[246:247], v[2:3] op_sel:[0,1,0] op_sel_hi:[1,1,1]
	ds_read_b32 v236, v19 offset:1024
	ds_read_b32 v237, v19 offset:5120
	ds_read_b32 v238, v19 offset:9216
	ds_read_b32 v239, v19 offset:1152
	ds_read_b32 v240, v19 offset:5248
	ds_read_b32 v241, v19 offset:9344
	ds_read_b32 v242, v19 offset:1280
	ds_read_b32 v243, v19 offset:5376
	ds_read_b32 v244, v19 offset:9472
	ds_read_b32 v245, v19 offset:1408
	ds_read_b32 v246, v19 offset:5504
	ds_read_b32 v247, v19 offset:9600
	s_waitcnt lgkmcnt(12)
	s_waitcnt vmcnt(27)
	v_pk_fma_f32 v[4:5], v[32:33], v[210:211], v[4:5] op_sel_hi:[1,0,1]
	v_pk_fma_f32 v[6:7], v[34:35], v[210:211], v[6:7] op_sel_hi:[1,0,1]
	v_pk_fma_f32 v[8:9], v[32:33], v[210:211], v[8:9] op_sel:[0,1,0] op_sel_hi:[1,1,1]
	v_pk_fma_f32 v[10:11], v[34:35], v[210:211], v[10:11] op_sel:[0,1,0] op_sel_hi:[1,1,1]
	v_pk_fma_f32 v[0:1], v[32:33], v[248:249], v[0:1] op_sel_hi:[1,0,1]
	v_pk_fma_f32 v[2:3], v[34:35], v[248:249], v[2:3] op_sel_hi:[1,0,1]
	s_waitcnt vmcnt(26)
	v_pk_fma_f32 v[4:5], v[36:37], v[248:249], v[4:5] op_sel:[0,1,0] op_sel_hi:[1,1,1]
	v_pk_fma_f32 v[6:7], v[38:39], v[248:249], v[6:7] op_sel:[0,1,0] op_sel_hi:[1,1,1]
	v_pk_fma_f32 v[8:9], v[36:37], v[160:161], v[8:9] op_sel_hi:[1,0,1]
	v_pk_fma_f32 v[10:11], v[38:39], v[160:161], v[10:11] op_sel_hi:[1,0,1]
	v_pk_fma_f32 v[0:1], v[36:37], v[162:163], v[0:1] op_sel_hi:[1,0,1]
	v_pk_fma_f32 v[2:3], v[38:39], v[162:163], v[2:3] op_sel_hi:[1,0,1]
	s_waitcnt vmcnt(25)
	v_pk_fma_f32 v[4:5], v[40:41], v[72:73], v[4:5] op_sel_hi:[1,0,1]
	v_pk_fma_f32 v[6:7], v[42:43], v[72:73], v[6:7] op_sel_hi:[1,0,1]
	v_pk_fma_f32 v[8:9], v[40:41], v[74:75], v[8:9] op_sel_hi:[1,0,1]
	v_pk_fma_f32 v[10:11], v[42:43], v[74:75], v[10:11] op_sel_hi:[1,0,1]
	v_pk_fma_f32 v[0:1], v[40:41], v[78:79], v[0:1] op_sel_hi:[1,0,1]
	v_pk_fma_f32 v[2:3], v[42:43], v[78:79], v[2:3] op_sel_hi:[1,0,1]
	s_waitcnt vmcnt(24)
	v_pk_fma_f32 v[4:5], v[44:45], v[96:97], v[4:5] op_sel_hi:[1,0,1]
	v_pk_fma_f32 v[6:7], v[46:47], v[96:97], v[6:7] op_sel_hi:[1,0,1]
	v_pk_fma_f32 v[8:9], v[44:45], v[98:99], v[8:9] op_sel_hi:[1,0,1]
	v_pk_fma_f32 v[10:11], v[46:47], v[98:99], v[10:11] op_sel_hi:[1,0,1]
	v_pk_fma_f32 v[0:1], v[44:45], v[100:101], v[0:1] op_sel_hi:[1,0,1]
	v_pk_fma_f32 v[2:3], v[46:47], v[100:101], v[2:3] op_sel_hi:[1,0,1]
	ds_read_b32 v210, v19 offset:1536
	ds_read_b32 v211, v19 offset:5632
	ds_read_b32 v248, v19 offset:9728
	ds_read_b32 v249, v19 offset:1664
	ds_read_b32 v160, v19 offset:5760
	ds_read_b32 v162, v19 offset:9856
	ds_read_b32 v72, v19 offset:1792
	ds_read_b32 v74, v19 offset:5888
	ds_read_b32 v78, v19 offset:9984
	ds_read_b32 v96, v19 offset:1920
	ds_read_b32 v98, v19 offset:6016
	ds_read_b32 v100, v19 offset:10112
	s_waitcnt lgkmcnt(12)
	s_waitcnt vmcnt(23)
	v_pk_fma_f32 v[4:5], v[48:49], v[236:237], v[4:5] op_sel_hi:[1,0,1]
	v_pk_fma_f32 v[6:7], v[50:51], v[236:237], v[6:7] op_sel_hi:[1,0,1]
	v_pk_fma_f32 v[8:9], v[48:49], v[236:237], v[8:9] op_sel:[0,1,0] op_sel_hi:[1,1,1]
	v_pk_fma_f32 v[10:11], v[50:51], v[236:237], v[10:11] op_sel:[0,1,0] op_sel_hi:[1,1,1]
	v_pk_fma_f32 v[0:1], v[48:49], v[238:239], v[0:1] op_sel_hi:[1,0,1]
	v_pk_fma_f32 v[2:3], v[50:51], v[238:239], v[2:3] op_sel_hi:[1,0,1]
	s_waitcnt vmcnt(22)
	v_pk_fma_f32 v[4:5], v[52:53], v[238:239], v[4:5] op_sel:[0,1,0] op_sel_hi:[1,1,1]
	v_pk_fma_f32 v[6:7], v[54:55], v[238:239], v[6:7] op_sel:[0,1,0] op_sel_hi:[1,1,1]
	v_pk_fma_f32 v[8:9], v[52:53], v[240:241], v[8:9] op_sel_hi:[1,0,1]
	v_pk_fma_f32 v[10:11], v[54:55], v[240:241], v[10:11] op_sel_hi:[1,0,1]
	v_pk_fma_f32 v[0:1], v[52:53], v[240:241], v[0:1] op_sel:[0,1,0] op_sel_hi:[1,1,1]
	v_pk_fma_f32 v[2:3], v[54:55], v[240:241], v[2:3] op_sel:[0,1,0] op_sel_hi:[1,1,1]
	s_waitcnt vmcnt(21)
	v_pk_fma_f32 v[4:5], v[56:57], v[242:243], v[4:5] op_sel_hi:[1,0,1]
	v_pk_fma_f32 v[6:7], v[58:59], v[242:243], v[6:7] op_sel_hi:[1,0,1]
	v_pk_fma_f32 v[8:9], v[56:57], v[242:243], v[8:9] op_sel:[0,1,0] op_sel_hi:[1,1,1]
	v_pk_fma_f32 v[10:11], v[58:59], v[242:243], v[10:11] op_sel:[0,1,0] op_sel_hi:[1,1,1]
	v_pk_fma_f32 v[0:1], v[56:57], v[244:245], v[0:1] op_sel_hi:[1,0,1]
	v_pk_fma_f32 v[2:3], v[58:59], v[244:245], v[2:3] op_sel_hi:[1,0,1]
	s_waitcnt vmcnt(20)
	v_pk_fma_f32 v[4:5], v[60:61], v[244:245], v[4:5] op_sel:[0,1,0] op_sel_hi:[1,1,1]
	v_pk_fma_f32 v[6:7], v[62:63], v[244:245], v[6:7] op_sel:[0,1,0] op_sel_hi:[1,1,1]
	v_pk_fma_f32 v[8:9], v[60:61], v[246:247], v[8:9] op_sel_hi:[1,0,1]
	v_pk_fma_f32 v[10:11], v[62:63], v[246:247], v[10:11] op_sel_hi:[1,0,1]
	v_pk_fma_f32 v[0:1], v[60:61], v[246:247], v[0:1] op_sel:[0,1,0] op_sel_hi:[1,1,1]
	v_pk_fma_f32 v[2:3], v[62:63], v[246:247], v[2:3] op_sel:[0,1,0] op_sel_hi:[1,1,1]
	ds_read_b32 v236, v19 offset:2048
	ds_read_b32 v237, v19 offset:6144
	ds_read_b32 v238, v19 offset:10240
	ds_read_b32 v239, v19 offset:2176
	ds_read_b32 v240, v19 offset:6272
	ds_read_b32 v241, v19 offset:10368
	ds_read_b32 v242, v19 offset:2304
	ds_read_b32 v243, v19 offset:6400
	ds_read_b32 v244, v19 offset:10496
	ds_read_b32 v245, v19 offset:2432
	ds_read_b32 v246, v19 offset:6528
	ds_read_b32 v247, v19 offset:10624
	s_waitcnt lgkmcnt(12)
	s_waitcnt vmcnt(19)
	v_pk_fma_f32 v[4:5], v[64:65], v[210:211], v[4:5] op_sel_hi:[1,0,1]
	v_pk_fma_f32 v[6:7], v[66:67], v[210:211], v[6:7] op_sel_hi:[1,0,1]
	v_pk_fma_f32 v[8:9], v[64:65], v[210:211], v[8:9] op_sel:[0,1,0] op_sel_hi:[1,1,1]
	v_pk_fma_f32 v[10:11], v[66:67], v[210:211], v[10:11] op_sel:[0,1,0] op_sel_hi:[1,1,1]
	v_pk_fma_f32 v[0:1], v[64:65], v[248:249], v[0:1] op_sel_hi:[1,0,1]
	v_pk_fma_f32 v[2:3], v[66:67], v[248:249], v[2:3] op_sel_hi:[1,0,1]
	s_waitcnt vmcnt(18)
	v_pk_fma_f32 v[4:5], v[68:69], v[248:249], v[4:5] op_sel:[0,1,0] op_sel_hi:[1,1,1]
	v_pk_fma_f32 v[6:7], v[70:71], v[248:249], v[6:7] op_sel:[0,1,0] op_sel_hi:[1,1,1]
	v_pk_fma_f32 v[8:9], v[68:69], v[160:161], v[8:9] op_sel_hi:[1,0,1]
	v_pk_fma_f32 v[10:11], v[70:71], v[160:161], v[10:11] op_sel_hi:[1,0,1]
	v_pk_fma_f32 v[0:1], v[68:69], v[162:163], v[0:1] op_sel_hi:[1,0,1]
	v_pk_fma_f32 v[2:3], v[70:71], v[162:163], v[2:3] op_sel_hi:[1,0,1]
	s_waitcnt vmcnt(17)
	v_pk_fma_f32 v[4:5], v[152:153], v[72:73], v[4:5] op_sel_hi:[1,0,1]
	v_pk_fma_f32 v[6:7], v[154:155], v[72:73], v[6:7] op_sel_hi:[1,0,1]
	v_pk_fma_f32 v[8:9], v[152:153], v[74:75], v[8:9] op_sel_hi:[1,0,1]
	v_pk_fma_f32 v[10:11], v[154:155], v[74:75], v[10:11] op_sel_hi:[1,0,1]
	v_pk_fma_f32 v[0:1], v[152:153], v[78:79], v[0:1] op_sel_hi:[1,0,1]
	v_pk_fma_f32 v[2:3], v[154:155], v[78:79], v[2:3] op_sel_hi:[1,0,1]
	s_waitcnt vmcnt(16)
	v_pk_fma_f32 v[4:5], v[156:157], v[96:97], v[4:5] op_sel_hi:[1,0,1]
	v_pk_fma_f32 v[6:7], v[158:159], v[96:97], v[6:7] op_sel_hi:[1,0,1]
	v_pk_fma_f32 v[8:9], v[156:157], v[98:99], v[8:9] op_sel_hi:[1,0,1]
	v_pk_fma_f32 v[10:11], v[158:159], v[98:99], v[10:11] op_sel_hi:[1,0,1]
	v_pk_fma_f32 v[0:1], v[156:157], v[100:101], v[0:1] op_sel_hi:[1,0,1]
	v_pk_fma_f32 v[2:3], v[158:159], v[100:101], v[2:3] op_sel_hi:[1,0,1]
	ds_read_b32 v210, v19 offset:2560
	ds_read_b32 v211, v19 offset:6656
	ds_read_b32 v248, v19 offset:10752
	ds_read_b32 v249, v19 offset:2688
	ds_read_b32 v160, v19 offset:6784
	ds_read_b32 v162, v19 offset:10880
	ds_read_b32 v72, v19 offset:2816
	ds_read_b32 v74, v19 offset:6912
	ds_read_b32 v78, v19 offset:11008
	ds_read_b32 v96, v19 offset:2944
	ds_read_b32 v98, v19 offset:7040
	ds_read_b32 v100, v19 offset:11136
	s_waitcnt lgkmcnt(12)
	s_waitcnt vmcnt(15)
	v_pk_fma_f32 v[4:5], v[164:165], v[236:237], v[4:5] op_sel_hi:[1,0,1]
	v_pk_fma_f32 v[6:7], v[166:167], v[236:237], v[6:7] op_sel_hi:[1,0,1]
	v_pk_fma_f32 v[8:9], v[164:165], v[236:237], v[8:9] op_sel:[0,1,0] op_sel_hi:[1,1,1]
	v_pk_fma_f32 v[10:11], v[166:167], v[236:237], v[10:11] op_sel:[0,1,0] op_sel_hi:[1,1,1]
	v_pk_fma_f32 v[0:1], v[164:165], v[238:239], v[0:1] op_sel_hi:[1,0,1]
	v_pk_fma_f32 v[2:3], v[166:167], v[238:239], v[2:3] op_sel_hi:[1,0,1]
	s_waitcnt vmcnt(14)
	v_pk_fma_f32 v[4:5], v[168:169], v[238:239], v[4:5] op_sel:[0,1,0] op_sel_hi:[1,1,1]
	v_pk_fma_f32 v[6:7], v[170:171], v[238:239], v[6:7] op_sel:[0,1,0] op_sel_hi:[1,1,1]
	v_pk_fma_f32 v[8:9], v[168:169], v[240:241], v[8:9] op_sel_hi:[1,0,1]
	v_pk_fma_f32 v[10:11], v[170:171], v[240:241], v[10:11] op_sel_hi:[1,0,1]
	v_pk_fma_f32 v[0:1], v[168:169], v[240:241], v[0:1] op_sel:[0,1,0] op_sel_hi:[1,1,1]
	v_pk_fma_f32 v[2:3], v[170:171], v[240:241], v[2:3] op_sel:[0,1,0] op_sel_hi:[1,1,1]
	s_waitcnt vmcnt(13)
	v_pk_fma_f32 v[4:5], v[172:173], v[242:243], v[4:5] op_sel_hi:[1,0,1]
	v_pk_fma_f32 v[6:7], v[174:175], v[242:243], v[6:7] op_sel_hi:[1,0,1]
	v_pk_fma_f32 v[8:9], v[172:173], v[242:243], v[8:9] op_sel:[0,1,0] op_sel_hi:[1,1,1]
	v_pk_fma_f32 v[10:11], v[174:175], v[242:243], v[10:11] op_sel:[0,1,0] op_sel_hi:[1,1,1]
	v_pk_fma_f32 v[0:1], v[172:173], v[244:245], v[0:1] op_sel_hi:[1,0,1]
	v_pk_fma_f32 v[2:3], v[174:175], v[244:245], v[2:3] op_sel_hi:[1,0,1]
	s_waitcnt vmcnt(12)
	v_pk_fma_f32 v[4:5], v[176:177], v[244:245], v[4:5] op_sel:[0,1,0] op_sel_hi:[1,1,1]
	v_pk_fma_f32 v[6:7], v[178:179], v[244:245], v[6:7] op_sel:[0,1,0] op_sel_hi:[1,1,1]
	v_pk_fma_f32 v[8:9], v[176:177], v[246:247], v[8:9] op_sel_hi:[1,0,1]
	v_pk_fma_f32 v[10:11], v[178:179], v[246:247], v[10:11] op_sel_hi:[1,0,1]
	v_pk_fma_f32 v[0:1], v[176:177], v[246:247], v[0:1] op_sel:[0,1,0] op_sel_hi:[1,1,1]
	v_pk_fma_f32 v[2:3], v[178:179], v[246:247], v[2:3] op_sel:[0,1,0] op_sel_hi:[1,1,1]
	ds_read_b32 v236, v19 offset:3072
	ds_read_b32 v237, v19 offset:7168
	ds_read_b32 v238, v19 offset:11264
	ds_read_b32 v239, v19 offset:3200
	ds_read_b32 v240, v19 offset:7296
	ds_read_b32 v241, v19 offset:11392
	ds_read_b32 v242, v19 offset:3328
	ds_read_b32 v243, v19 offset:7424
	ds_read_b32 v244, v19 offset:11520
	ds_read_b32 v245, v19 offset:3456
	ds_read_b32 v246, v19 offset:7552
	ds_read_b32 v247, v19 offset:11648
	s_waitcnt lgkmcnt(12)
	s_waitcnt vmcnt(11)
	v_pk_fma_f32 v[4:5], v[180:181], v[210:211], v[4:5] op_sel_hi:[1,0,1]
	v_pk_fma_f32 v[6:7], v[182:183], v[210:211], v[6:7] op_sel_hi:[1,0,1]
	v_pk_fma_f32 v[8:9], v[180:181], v[210:211], v[8:9] op_sel:[0,1,0] op_sel_hi:[1,1,1]
	v_pk_fma_f32 v[10:11], v[182:183], v[210:211], v[10:11] op_sel:[0,1,0] op_sel_hi:[1,1,1]
	v_pk_fma_f32 v[0:1], v[180:181], v[248:249], v[0:1] op_sel_hi:[1,0,1]
	v_pk_fma_f32 v[2:3], v[182:183], v[248:249], v[2:3] op_sel_hi:[1,0,1]
	s_waitcnt vmcnt(10)
	v_pk_fma_f32 v[4:5], v[184:185], v[248:249], v[4:5] op_sel:[0,1,0] op_sel_hi:[1,1,1]
	v_pk_fma_f32 v[6:7], v[186:187], v[248:249], v[6:7] op_sel:[0,1,0] op_sel_hi:[1,1,1]
	v_pk_fma_f32 v[8:9], v[184:185], v[160:161], v[8:9] op_sel_hi:[1,0,1]
	v_pk_fma_f32 v[10:11], v[186:187], v[160:161], v[10:11] op_sel_hi:[1,0,1]
	v_pk_fma_f32 v[0:1], v[184:185], v[162:163], v[0:1] op_sel_hi:[1,0,1]
	v_pk_fma_f32 v[2:3], v[186:187], v[162:163], v[2:3] op_sel_hi:[1,0,1]
	s_waitcnt vmcnt(9)
	v_pk_fma_f32 v[4:5], v[188:189], v[72:73], v[4:5] op_sel_hi:[1,0,1]
	v_pk_fma_f32 v[6:7], v[190:191], v[72:73], v[6:7] op_sel_hi:[1,0,1]
	v_pk_fma_f32 v[8:9], v[188:189], v[74:75], v[8:9] op_sel_hi:[1,0,1]
	v_pk_fma_f32 v[10:11], v[190:191], v[74:75], v[10:11] op_sel_hi:[1,0,1]
	v_pk_fma_f32 v[0:1], v[188:189], v[78:79], v[0:1] op_sel_hi:[1,0,1]
	v_pk_fma_f32 v[2:3], v[190:191], v[78:79], v[2:3] op_sel_hi:[1,0,1]
	s_waitcnt vmcnt(8)
	v_pk_fma_f32 v[4:5], v[192:193], v[96:97], v[4:5] op_sel_hi:[1,0,1]
	v_pk_fma_f32 v[6:7], v[194:195], v[96:97], v[6:7] op_sel_hi:[1,0,1]
	v_pk_fma_f32 v[8:9], v[192:193], v[98:99], v[8:9] op_sel_hi:[1,0,1]
	v_pk_fma_f32 v[10:11], v[194:195], v[98:99], v[10:11] op_sel_hi:[1,0,1]
	v_pk_fma_f32 v[0:1], v[192:193], v[100:101], v[0:1] op_sel_hi:[1,0,1]
	v_pk_fma_f32 v[2:3], v[194:195], v[100:101], v[2:3] op_sel_hi:[1,0,1]
	ds_read_b32 v210, v19 offset:3584
	ds_read_b32 v211, v19 offset:7680
	ds_read_b32 v248, v19 offset:11776
	ds_read_b32 v249, v19 offset:3712
	ds_read_b32 v160, v19 offset:7808
	ds_read_b32 v162, v19 offset:11904
	ds_read_b32 v72, v19 offset:3840
	ds_read_b32 v74, v19 offset:7936
	ds_read_b32 v78, v19 offset:12032
	ds_read_b32 v96, v19 offset:3968
	ds_read_b32 v98, v19 offset:8064
	ds_read_b32 v100, v19 offset:12160
	s_waitcnt lgkmcnt(12)
	s_waitcnt vmcnt(7)
	v_pk_fma_f32 v[4:5], v[196:197], v[236:237], v[4:5] op_sel_hi:[1,0,1]
	v_pk_fma_f32 v[6:7], v[198:199], v[236:237], v[6:7] op_sel_hi:[1,0,1]
	v_pk_fma_f32 v[8:9], v[196:197], v[236:237], v[8:9] op_sel:[0,1,0] op_sel_hi:[1,1,1]
	v_pk_fma_f32 v[10:11], v[198:199], v[236:237], v[10:11] op_sel:[0,1,0] op_sel_hi:[1,1,1]
	v_pk_fma_f32 v[0:1], v[196:197], v[238:239], v[0:1] op_sel_hi:[1,0,1]
	v_pk_fma_f32 v[2:3], v[198:199], v[238:239], v[2:3] op_sel_hi:[1,0,1]
	s_waitcnt vmcnt(6)
	v_pk_fma_f32 v[4:5], v[200:201], v[238:239], v[4:5] op_sel:[0,1,0] op_sel_hi:[1,1,1]
	v_pk_fma_f32 v[6:7], v[202:203], v[238:239], v[6:7] op_sel:[0,1,0] op_sel_hi:[1,1,1]
	v_pk_fma_f32 v[8:9], v[200:201], v[240:241], v[8:9] op_sel_hi:[1,0,1]
	v_pk_fma_f32 v[10:11], v[202:203], v[240:241], v[10:11] op_sel_hi:[1,0,1]
	v_pk_fma_f32 v[0:1], v[200:201], v[240:241], v[0:1] op_sel:[0,1,0] op_sel_hi:[1,1,1]
	v_pk_fma_f32 v[2:3], v[202:203], v[240:241], v[2:3] op_sel:[0,1,0] op_sel_hi:[1,1,1]
	s_waitcnt vmcnt(5)
	v_pk_fma_f32 v[4:5], v[204:205], v[242:243], v[4:5] op_sel_hi:[1,0,1]
	v_pk_fma_f32 v[6:7], v[206:207], v[242:243], v[6:7] op_sel_hi:[1,0,1]
	v_pk_fma_f32 v[8:9], v[204:205], v[242:243], v[8:9] op_sel:[0,1,0] op_sel_hi:[1,1,1]
	v_pk_fma_f32 v[10:11], v[206:207], v[242:243], v[10:11] op_sel:[0,1,0] op_sel_hi:[1,1,1]
	v_pk_fma_f32 v[0:1], v[204:205], v[244:245], v[0:1] op_sel_hi:[1,0,1]
	v_pk_fma_f32 v[2:3], v[206:207], v[244:245], v[2:3] op_sel_hi:[1,0,1]
	s_waitcnt vmcnt(4)
	v_pk_fma_f32 v[4:5], v[212:213], v[244:245], v[4:5] op_sel:[0,1,0] op_sel_hi:[1,1,1]
	v_pk_fma_f32 v[6:7], v[214:215], v[244:245], v[6:7] op_sel:[0,1,0] op_sel_hi:[1,1,1]
	v_pk_fma_f32 v[8:9], v[212:213], v[246:247], v[8:9] op_sel_hi:[1,0,1]
	v_pk_fma_f32 v[10:11], v[214:215], v[246:247], v[10:11] op_sel_hi:[1,0,1]
	v_pk_fma_f32 v[0:1], v[212:213], v[246:247], v[0:1] op_sel:[0,1,0] op_sel_hi:[1,1,1]
	v_pk_fma_f32 v[2:3], v[214:215], v[246:247], v[2:3] op_sel:[0,1,0] op_sel_hi:[1,1,1]
	s_waitcnt lgkmcnt(0)
	s_waitcnt vmcnt(3)
	v_pk_fma_f32 v[4:5], v[220:221], v[210:211], v[4:5] op_sel_hi:[1,0,1]
	v_pk_fma_f32 v[6:7], v[222:223], v[210:211], v[6:7] op_sel_hi:[1,0,1]
	v_pk_fma_f32 v[8:9], v[220:221], v[210:211], v[8:9] op_sel:[0,1,0] op_sel_hi:[1,1,1]
	v_pk_fma_f32 v[10:11], v[222:223], v[210:211], v[10:11] op_sel:[0,1,0] op_sel_hi:[1,1,1]
	v_pk_fma_f32 v[0:1], v[220:221], v[248:249], v[0:1] op_sel_hi:[1,0,1]
	v_pk_fma_f32 v[2:3], v[222:223], v[248:249], v[2:3] op_sel_hi:[1,0,1]
	s_waitcnt vmcnt(2)
	v_pk_fma_f32 v[4:5], v[224:225], v[248:249], v[4:5] op_sel:[0,1,0] op_sel_hi:[1,1,1]
	v_pk_fma_f32 v[6:7], v[226:227], v[248:249], v[6:7] op_sel:[0,1,0] op_sel_hi:[1,1,1]
	v_pk_fma_f32 v[8:9], v[224:225], v[160:161], v[8:9] op_sel_hi:[1,0,1]
	v_pk_fma_f32 v[10:11], v[226:227], v[160:161], v[10:11] op_sel_hi:[1,0,1]
	v_pk_fma_f32 v[0:1], v[224:225], v[162:163], v[0:1] op_sel_hi:[1,0,1]
	v_pk_fma_f32 v[2:3], v[226:227], v[162:163], v[2:3] op_sel_hi:[1,0,1]
	s_waitcnt vmcnt(1)
	v_pk_fma_f32 v[4:5], v[228:229], v[72:73], v[4:5] op_sel_hi:[1,0,1]
	v_pk_fma_f32 v[6:7], v[230:231], v[72:73], v[6:7] op_sel_hi:[1,0,1]
	v_pk_fma_f32 v[8:9], v[228:229], v[74:75], v[8:9] op_sel_hi:[1,0,1]
	v_pk_fma_f32 v[10:11], v[230:231], v[74:75], v[10:11] op_sel_hi:[1,0,1]
	v_pk_fma_f32 v[0:1], v[228:229], v[78:79], v[0:1] op_sel_hi:[1,0,1]
	v_pk_fma_f32 v[2:3], v[230:231], v[78:79], v[2:3] op_sel_hi:[1,0,1]
	s_waitcnt vmcnt(0)
	v_pk_fma_f32 v[4:5], v[232:233], v[96:97], v[4:5] op_sel_hi:[1,0,1]
	v_pk_fma_f32 v[6:7], v[234:235], v[96:97], v[6:7] op_sel_hi:[1,0,1]
	v_pk_fma_f32 v[8:9], v[232:233], v[98:99], v[8:9] op_sel_hi:[1,0,1]
	v_pk_fma_f32 v[10:11], v[234:235], v[98:99], v[10:11] op_sel_hi:[1,0,1]
	v_pk_fma_f32 v[0:1], v[232:233], v[100:101], v[0:1] op_sel_hi:[1,0,1]
	v_pk_fma_f32 v[2:3], v[234:235], v[100:101], v[2:3] op_sel_hi:[1,0,1]
	ds_write_b128 v127, v[4:7] offset:12288
	ds_write_b128 v127, v[8:11] offset:12304
	ds_write_b128 v127, v[0:3] offset:12320
	s_waitcnt lgkmcnt(0)
	s_barrier
	s_and_saveexec_b64 s[42:43], s[78:79]
	s_cbranch_execz .LBB0_75
	s_and_b64 s[0:1], s[40:41], exec
	s_cselect_b32 s0, 0x1800, 0
	s_add_i32 s0, s38, s0
	v_readlane_b32 s44, v251, 26
	v_or_b32_e32 v78, s0, v81
	v_readlane_b32 s54, v251, 36
	v_readlane_b32 s55, v251, 37
	s_and_b64 s[0:1], s[40:41], exec
	s_cselect_b32 s0, 3, 0
	v_lshl_add_u64 v[0:1], v[78:79], 2, s[54:55]
	global_load_dword v34, v[0:1], off
	ds_read2st64_b32 v[0:1], v128 offset0:48 offset1:51
	ds_read2st64_b32 v[2:3], v128 offset0:54 offset1:57
	ds_read2st64_b32 v[4:5], v128 offset0:60 offset1:63
	ds_read2st64_b32 v[6:7], v128 offset0:66 offset1:69
	ds_read2st64_b32 v[8:9], v128 offset0:72 offset1:75
	ds_read2st64_b32 v[10:11], v128 offset0:78 offset1:81
	ds_read2st64_b32 v[12:13], v128 offset0:84 offset1:87
	ds_read2st64_b32 v[14:15], v128 offset0:90 offset1:93
	ds_read2st64_b32 v[16:17], v128 offset0:96 offset1:99
	ds_read2st64_b32 v[18:19], v128 offset0:102 offset1:105
	ds_read2st64_b32 v[20:21], v128 offset0:108 offset1:111
	ds_read2st64_b32 v[22:23], v128 offset0:114 offset1:117
	ds_read2st64_b32 v[24:25], v128 offset0:120 offset1:123
	ds_read2st64_b32 v[26:27], v128 offset0:126 offset1:129
	ds_read2st64_b32 v[28:29], v128 offset0:132 offset1:135
	ds_read2st64_b32 v[30:31], v128 offset0:138 offset1:141
	v_add_u32_e32 v32, s0, v83
	s_movk_i32 s0, 0x1800
	v_mul_lo_u32 v32, v32, s0
	v_readlane_b32 s45, v251, 27
	v_readlane_b32 s46, v251, 28
	v_readlane_b32 s47, v251, 29
	v_readlane_b32 s48, v251, 30
	v_readlane_b32 s49, v251, 31
	v_readlane_b32 s50, v251, 32
	v_readlane_b32 s51, v251, 33
	v_readlane_b32 s52, v251, 34
	v_readlane_b32 s53, v251, 35
	v_readlane_b32 s56, v251, 38
	v_readlane_b32 s57, v251, 39
	v_readlane_b32 s58, v251, 40
	v_readlane_b32 s59, v251, 41
	v_add_u32_e32 v32, s38, v32
	v_or_b32_e32 v32, v32, v81
	v_readlane_b32 s44, v251, 4
	v_ashrrev_i32_e32 v33, 31, v32
	v_readlane_b32 s58, v251, 18
	v_readlane_b32 s59, v251, 19
	v_readlane_b32 s45, v251, 5
	v_readlane_b32 s46, v251, 6
	v_readlane_b32 s47, v251, 7
	v_readlane_b32 s48, v251, 8
	v_readlane_b32 s49, v251, 9
	v_readlane_b32 s50, v251, 10
	v_readlane_b32 s51, v251, 11
	v_readlane_b32 s52, v251, 12
	v_readlane_b32 s53, v251, 13
	v_readlane_b32 s54, v251, 14
	v_readlane_b32 s55, v251, 15
	v_readlane_b32 s56, v251, 16
	v_readlane_b32 s57, v251, 17
	s_waitcnt vmcnt(0) lgkmcnt(14)
	v_add_f32_e32 v0, v34, v0
	v_add_f32_e32 v0, v0, v1
	v_add_f32_e32 v0, v0, v2
	v_add_f32_e32 v0, v0, v3
	s_waitcnt lgkmcnt(13)
	v_add_f32_e32 v0, v0, v4
	v_add_f32_e32 v0, v0, v5
	s_waitcnt lgkmcnt(12)
	v_add_f32_e32 v0, v0, v6
	v_add_f32_e32 v0, v0, v7
	s_waitcnt lgkmcnt(11)
	v_add_f32_e32 v0, v0, v8
	v_add_f32_e32 v0, v0, v9
	s_waitcnt lgkmcnt(10)
	v_add_f32_e32 v0, v0, v10
	v_add_f32_e32 v0, v0, v11
	s_waitcnt lgkmcnt(9)
	v_add_f32_e32 v0, v0, v12
	v_add_f32_e32 v0, v0, v13
	s_waitcnt lgkmcnt(8)
	v_add_f32_e32 v0, v0, v14
	v_add_f32_e32 v0, v0, v15
	s_waitcnt lgkmcnt(7)
	v_add_f32_e32 v0, v0, v16
	v_add_f32_e32 v0, v0, v17
	s_waitcnt lgkmcnt(6)
	v_add_f32_e32 v0, v0, v18
	v_add_f32_e32 v0, v0, v19
	s_waitcnt lgkmcnt(5)
	v_add_f32_e32 v0, v0, v20
	v_add_f32_e32 v0, v0, v21
	s_waitcnt lgkmcnt(4)
	v_add_f32_e32 v0, v0, v22
	v_add_f32_e32 v0, v0, v23
	s_waitcnt lgkmcnt(3)
	v_add_f32_e32 v0, v0, v24
	v_add_f32_e32 v0, v0, v25
	s_waitcnt lgkmcnt(2)
	v_add_f32_e32 v0, v0, v26
	v_add_f32_e32 v0, v0, v27
	s_waitcnt lgkmcnt(1)
	v_add_f32_e32 v0, v0, v28
	v_add_f32_e32 v0, v0, v29
	s_waitcnt lgkmcnt(0)
	v_add_f32_e32 v0, v0, v30
	v_add_f32_e32 v2, v0, v31
	v_lshl_add_u64 v[0:1], v[32:33], 2, s[58:59]
	global_store_dword v[0:1], v2, off
